# F and I residual GEMM epilogues: next row-group x loads prefetched one group ahead into spare registers (counted vmcnt)
# baseline (speedup 1.0000x reference)
.LBB0_1452:
	s_or_b64 exec, exec, s[26:27]
	s_waitcnt lgkmcnt(0)
	v_add_u32_e32 v136, s24, v230
	v_mul_hi_i32 v0, v136, s61
	v_lshrrev_b32_e32 v2, 31, v0
	v_ashrrev_i32_e32 v0, 11, v0
	v_add_u32_e32 v0, v0, v2
	v_mad_i32_i24 v3, v0, s48, v136
	v_cmp_lt_i32_e32 vcc, s49, v3
	s_and_saveexec_b64 s[26:27], vcc
	s_xor_b64 s[26:27], exec, s[26:27]
	v_lshlrev_b32_e32 v0, 12, v0
	s_movk_i32 s25, 0xff00
	v_add3_u32 v2, v0, v3, s25
	s_or_saveexec_b64 s[26:27], s[26:27]
	v_mov_b64_e32 v[132:133], s[12:13]
	s_xor_b64 exec, exec, s[26:27]
	v_lshl_add_u32 v2, v0, 8, v3
	v_mov_b64_e32 v[132:133], s[16:17]
	s_or_b64 exec, exec, s[26:27]
	v_ashrrev_i32_e32 v3, 31, v2
	v_lshlrev_b64 v[2:3], 12, v[2:3]
	v_lshl_add_u64 v[2:3], v[132:133], 0, v[2:3]
	v_ashrrev_i32_e32 v137, 31, v136
	v_lshl_add_u64 v[134:135], s[22:23], 2, v[2:3]
	v_lshlrev_b32_e32 v0, 2, v200
	v_lshlrev_b64 v[132:133], 11, v[136:137]
	v_lshl_add_u64 v[2:3], v[134:135], 0, v[0:1]
	v_lshlrev_b32_e32 v138, 2, v202
	v_mov_b32_e32 v139, v1
	v_lshl_add_u64 v[162:163], v[2:3], 0, v[138:139]
	v_lshl_add_u64 v[150:151], s[18:19], 0, v[132:133]
	v_add_u32_e32 v132, s22, v204
	v_lshlrev_b32_e32 v2, 2, v204
	v_mov_b32_e32 v3, v1
	v_add_u32_e32 v140, s56, v2
	v_ashrrev_i32_e32 v133, 31, v132
	v_lshl_add_u64 v[166:167], v[134:135], 0, v[2:3]
	v_lshl_add_u64 v[134:135], s[22:23], 0, v[204:205]
	ds_read_b128 v[142:145], v140 offset:1024
	ds_read_b128 v[146:149], v140 offset:2048
	v_lshl_add_u64 v[168:169], v[132:133], 1, v[150:151]
	v_lshl_add_u64 v[170:171], v[134:135], 1, v[150:151]
	s_waitcnt vmcnt(0)
	v_mov_b32_e32 v242, 0x10000
	v_mov_b32_e32 v243, 0
	v_mov_b32_e32 v244, 0x50000
	v_mov_b32_e32 v245, 0
	v_lshl_add_u64 v[240:241], v[162:163], 0, v[242:243]
	global_load_dwordx4 v[150:153], v[162:163], off offset:576
	global_load_dwordx4 v[154:157], v[162:163], off offset:512
	global_load_dwordx4 v[158:161], v[162:163], off offset:64
	s_nop 0
	global_load_dwordx4 v[162:165], v[162:163], off
	global_load_dwordx4 v[172:175], v[240:241], off
	global_load_dwordx4 v[176:179], v[240:241], off offset:64
	global_load_dwordx4 v[180:183], v[240:241], off offset:512
	global_load_dwordx4 v[184:187], v[240:241], off offset:576
	s_waitcnt vmcnt(4) lgkmcnt(0)
	v_pk_fma_f32 v[124:125], v[124:125], v[142:143], v[162:163]
	v_pk_fma_f32 v[126:127], v[126:127], v[144:145], v[164:165]
	v_pk_mul_f32 v[142:143], v[146:147], v[124:125]
	v_pk_mul_f32 v[144:145], v[148:149], v[126:127]
	v_cvt_pk_bf16_f32 v142, v142, v143
	v_cvt_pk_bf16_f32 v143, v144, v145
	global_store_dwordx4 v[166:167], v[124:127], off
	global_store_dwordx2 v[168:169], v[142:143], off
	v_pk_mul_f32 v[162:163], v[124:125], v[124:125]
	v_pk_mul_f32 v[146:147], v[126:127], v[126:127]
	ds_read_b128 v[124:127], v140 offset:1088
	ds_read_b128 v[142:145], v140 offset:2112
	v_add_f32_e32 v3, v162, v163
	v_add_f32_e32 v3, v146, v3
	v_add_f32_e32 v3, v147, v3
	s_waitcnt lgkmcnt(0)
	v_pk_fma_f32 v[116:117], v[116:117], v[124:125], v[158:159]
	v_pk_fma_f32 v[118:119], v[118:119], v[126:127], v[160:161]
	global_store_dwordx4 v[166:167], v[116:119], off offset:64
	v_pk_mul_f32 v[148:149], v[116:117], v[116:117]
	v_pk_mul_f32 v[158:159], v[118:119], v[118:119]
	v_pk_mul_f32 v[116:117], v[142:143], v[116:117]
	v_pk_mul_f32 v[118:119], v[144:145], v[118:119]
	v_cvt_pk_bf16_f32 v116, v116, v117
	v_cvt_pk_bf16_f32 v117, v118, v119
	global_store_dwordx2 v[170:171], v[116:117], off offset:32
	ds_read_b128 v[116:119], v140 offset:1536
	ds_read_b128 v[124:127], v140 offset:2560
	v_add_f32_e32 v139, v148, v149
	v_add_f32_e32 v139, v158, v139
	v_add_f32_e32 v139, v159, v139
	s_waitcnt lgkmcnt(0)
	v_pk_fma_f32 v[116:117], v[128:129], v[116:117], v[154:155]
	v_pk_fma_f32 v[118:119], v[130:131], v[118:119], v[156:157]
	global_store_dwordx4 v[166:167], v[116:119], off offset:512
	v_pk_mul_f32 v[128:129], v[116:117], v[116:117]
	v_pk_mul_f32 v[130:131], v[118:119], v[118:119]
	v_pk_mul_f32 v[116:117], v[124:125], v[116:117]
	v_pk_mul_f32 v[118:119], v[126:127], v[118:119]
	v_cvt_pk_bf16_f32 v116, v116, v117
	v_cvt_pk_bf16_f32 v117, v118, v119
	global_store_dwordx2 v[170:171], v[116:117], off offset:256
	ds_read_b128 v[116:119], v140 offset:1600
	ds_read_b128 v[124:127], v140 offset:2624
	v_add_f32_e32 v128, v128, v129
	v_add_f32_e32 v128, v130, v128
	v_add_f32_e32 v3, v3, v139
	s_waitcnt lgkmcnt(0)
	v_pk_fma_f32 v[116:117], v[120:121], v[116:117], v[150:151]
	v_pk_fma_f32 v[118:119], v[122:123], v[118:119], v[152:153]
	global_store_dwordx4 v[166:167], v[116:119], off offset:576
	v_pk_mul_f32 v[120:121], v[116:117], v[116:117]
	v_pk_mul_f32 v[122:123], v[118:119], v[118:119]
	v_pk_mul_f32 v[116:117], v[124:125], v[116:117]
	v_pk_mul_f32 v[118:119], v[126:127], v[118:119]
	v_cvt_pk_bf16_f32 v116, v116, v117
	v_cvt_pk_bf16_f32 v117, v118, v119
	global_store_dwordx2 v[170:171], v[116:117], off offset:288
	v_and_b32_e32 v117, 64, v208
	v_add_f32_e32 v120, v120, v121
	v_xor_b32_e32 v116, 16, v208
	v_add_u32_e32 v117, 64, v117
	v_add_f32_e32 v128, v131, v128
	v_add_f32_e32 v120, v122, v120
	v_cmp_lt_i32_e32 vcc, v116, v117
	v_add_f32_e32 v3, v3, v128
	v_add_f32_e32 v120, v123, v120
	v_cndmask_b32_e32 v116, v208, v116, vcc
	v_add_f32_e32 v3, v3, v120
	v_lshlrev_b32_e32 v122, 2, v116
	ds_bpermute_b32 v116, v122, v3
	s_waitcnt lgkmcnt(0)
	v_add_f32_e32 v3, v3, v116
	v_xor_b32_e32 v116, 32, v208
	v_cmp_lt_i32_e32 vcc, v116, v117
	s_nop 1
	v_cndmask_b32_e32 v116, v208, v116, vcc
	v_lshlrev_b32_e32 v123, 2, v116
	ds_bpermute_b32 v116, v123, v3
	s_and_saveexec_b64 s[26:27], s[6:7]
	s_cbranch_execz .LBB0_1458
	s_waitcnt lgkmcnt(0)
	v_add_f32_e32 v3, v3, v116
	v_lshl_add_u64 v[116:117], v[136:137], 2, s[20:21]
	global_atomic_add_f32 v[116:117], v3, off
.LBB0_1458:
	s_or_b64 exec, exec, s[26:27]
	s_waitcnt lgkmcnt(0)
	v_add_u32_e32 v116, 16, v136
	v_mul_hi_i32 v3, v116, s61
	v_lshrrev_b32_e32 v117, 31, v3
	v_ashrrev_i32_e32 v3, 11, v3
	v_add_u32_e32 v3, v3, v117
	v_mad_i32_i24 v117, v3, s48, v116
	v_cmp_lt_i32_e32 vcc, s49, v117
	s_and_saveexec_b64 s[26:27], vcc
	s_xor_b64 s[26:27], exec, s[26:27]
	v_lshlrev_b32_e32 v3, 12, v3
	s_movk_i32 s25, 0xff00
	v_add3_u32 v118, v3, v117, s25
	s_or_saveexec_b64 s[26:27], s[26:27]
	v_mov_b64_e32 v[120:121], s[12:13]
	s_xor_b64 exec, exec, s[26:27]
	v_lshl_add_u32 v118, v3, 8, v117
	v_mov_b64_e32 v[120:121], s[16:17]
	s_or_b64 exec, exec, s[26:27]
	v_ashrrev_i32_e32 v119, 31, v118
	v_lshlrev_b64 v[118:119], 12, v[118:119]
	v_lshl_add_u64 v[118:119], v[120:121], 0, v[118:119]
	v_lshl_add_u64 v[154:155], s[22:23], 2, v[118:119]
	v_lshl_add_u64 v[118:119], v[154:155], 0, v[0:1]
	v_mov_b32_e32 v139, v1
	v_lshl_add_u64 v[142:143], v[118:119], 0, v[138:139]
	v_lshl_add_u64 v[240:241], v[142:143], 0, v[242:243]
	global_load_dwordx4 v[188:191], v[240:241], off
	global_load_dwordx4 v[192:195], v[240:241], off offset:64
	global_load_dwordx4 v[212:215], v[240:241], off offset:512
	global_load_dwordx4 v[216:219], v[240:241], off offset:576
	s_nop 0
	ds_read_b128 v[146:149], v140 offset:1024
	ds_read_b128 v[150:153], v140 offset:2048
	v_ashrrev_i32_e32 v117, 31, v116
	v_mov_b32_e32 v3, v1
	v_lshlrev_b64 v[156:157], 11, v[116:117]
	v_lshl_add_u64 v[156:157], s[18:19], 0, v[156:157]
	v_lshl_add_u64 v[154:155], v[154:155], 0, v[2:3]
	v_lshl_add_u64 v[158:159], v[132:133], 1, v[156:157]
	v_lshl_add_u64 v[156:157], v[134:135], 1, v[156:157]
	s_waitcnt vmcnt(4) lgkmcnt(0)
	v_mov_b64_e32 v[118:119], v[172:173]
	v_mov_b64_e32 v[120:121], v[174:175]
	v_mov_b64_e32 v[124:125], v[176:177]
	v_mov_b64_e32 v[126:127], v[178:179]
	v_mov_b64_e32 v[128:129], v[180:181]
	v_mov_b64_e32 v[130:131], v[182:183]
	v_mov_b64_e32 v[142:143], v[184:185]
	v_mov_b64_e32 v[144:145], v[186:187]
	v_pk_fma_f32 v[112:113], v[112:113], v[146:147], v[118:119]
	v_pk_fma_f32 v[114:115], v[114:115], v[148:149], v[120:121]
	v_pk_mul_f32 v[120:121], v[150:151], v[112:113]
	v_pk_mul_f32 v[148:149], v[152:153], v[114:115]
	v_pk_mul_f32 v[118:119], v[112:113], v[112:113]
	global_store_dwordx4 v[154:155], v[112:115], off
	v_pk_mul_f32 v[146:147], v[114:115], v[114:115]
	v_add_f32_e32 v3, v118, v119
	v_cvt_pk_bf16_f32 v112, v120, v121
	v_cvt_pk_bf16_f32 v113, v148, v149
	global_store_dwordx2 v[158:159], v[112:113], off
	ds_read_b128 v[112:115], v140 offset:1088
	ds_read_b128 v[118:121], v140 offset:2112
	v_add_f32_e32 v3, v146, v3
	v_add_f32_e32 v3, v147, v3
	s_waitcnt lgkmcnt(0)
	v_pk_fma_f32 v[104:105], v[104:105], v[112:113], v[124:125]
	v_pk_fma_f32 v[106:107], v[106:107], v[114:115], v[126:127]
	global_store_dwordx4 v[154:155], v[104:107], off offset:64
	v_pk_mul_f32 v[112:113], v[104:105], v[104:105]
	v_pk_mul_f32 v[124:125], v[106:107], v[106:107]
	v_pk_mul_f32 v[104:105], v[118:119], v[104:105]
	v_pk_mul_f32 v[106:107], v[120:121], v[106:107]
	v_cvt_pk_bf16_f32 v104, v104, v105
	v_cvt_pk_bf16_f32 v105, v106, v107
	global_store_dwordx2 v[156:157], v[104:105], off offset:32
	v_add_f32_e32 v112, v112, v113
	ds_read_b128 v[104:107], v140 offset:1536
	v_add_f32_e32 v118, v124, v112
	ds_read_b128 v[112:115], v140 offset:2560
	v_add_f32_e32 v118, v125, v118
	v_add_f32_e32 v3, v3, v118
	s_waitcnt lgkmcnt(0)
	v_pk_fma_f32 v[104:105], v[108:109], v[104:105], v[128:129]
	v_pk_fma_f32 v[106:107], v[110:111], v[106:107], v[130:131]
	global_store_dwordx4 v[154:155], v[104:107], off offset:512
	v_pk_mul_f32 v[108:109], v[104:105], v[104:105]
	v_pk_mul_f32 v[118:119], v[106:107], v[106:107]
	v_pk_mul_f32 v[104:105], v[112:113], v[104:105]
	v_pk_mul_f32 v[106:107], v[114:115], v[106:107]
	v_cvt_pk_bf16_f32 v104, v104, v105
	v_cvt_pk_bf16_f32 v105, v106, v107
	global_store_dwordx2 v[156:157], v[104:105], off offset:256
	ds_read_b128 v[104:107], v140 offset:1600
	v_add_f32_e32 v108, v108, v109
	v_add_f32_e32 v112, v118, v108
	ds_read_b128 v[108:111], v140 offset:2624
	v_add_f32_e32 v112, v119, v112
	s_waitcnt lgkmcnt(0)
	v_pk_fma_f32 v[100:101], v[100:101], v[104:105], v[142:143]
	v_pk_fma_f32 v[102:103], v[102:103], v[106:107], v[144:145]
	v_pk_mul_f32 v[104:105], v[100:101], v[100:101]
	v_pk_mul_f32 v[106:107], v[102:103], v[102:103]
	v_add_f32_e32 v104, v104, v105
	v_add_f32_e32 v104, v106, v104
	v_add_f32_e32 v3, v3, v112
	v_add_f32_e32 v104, v107, v104
	v_add_f32_e32 v3, v3, v104
	ds_bpermute_b32 v106, v122, v3
	global_store_dwordx4 v[154:155], v[100:103], off offset:576
	v_pk_mul_f32 v[104:105], v[108:109], v[100:101]
	s_waitcnt lgkmcnt(0)
	v_add_f32_e32 v3, v3, v106
	ds_bpermute_b32 v100, v123, v3
	v_pk_mul_f32 v[102:103], v[110:111], v[102:103]
	v_cvt_pk_bf16_f32 v104, v104, v105
	v_cvt_pk_bf16_f32 v105, v102, v103
	global_store_dwordx2 v[156:157], v[104:105], off offset:288
	s_and_saveexec_b64 s[26:27], s[6:7]
	s_cbranch_execz .LBB0_1464
	s_waitcnt lgkmcnt(0)
	v_add_f32_e32 v3, v3, v100
	v_lshl_add_u64 v[100:101], v[116:117], 2, s[20:21]
	global_atomic_add_f32 v[100:101], v3, off
.LBB0_1464:
	s_or_b64 exec, exec, s[26:27]
	s_waitcnt lgkmcnt(0)
	v_add_u32_e32 v100, 32, v136
	v_mul_hi_i32 v3, v100, s61
	v_lshrrev_b32_e32 v101, 31, v3
	v_ashrrev_i32_e32 v3, 11, v3
	v_add_u32_e32 v3, v3, v101
	v_mad_i32_i24 v101, v3, s48, v100
	v_cmp_lt_i32_e32 vcc, s49, v101
	s_and_saveexec_b64 s[26:27], vcc
	s_xor_b64 s[26:27], exec, s[26:27]
	v_lshlrev_b32_e32 v3, 12, v3
	s_movk_i32 s25, 0xff00
	v_add3_u32 v102, v3, v101, s25
	s_or_saveexec_b64 s[26:27], s[26:27]
	v_mov_b64_e32 v[104:105], s[12:13]
	s_xor_b64 exec, exec, s[26:27]
	v_lshl_add_u32 v102, v3, 8, v101
	v_mov_b64_e32 v[104:105], s[16:17]
	s_or_b64 exec, exec, s[26:27]
	v_ashrrev_i32_e32 v103, 31, v102
	v_lshlrev_b64 v[102:103], 12, v[102:103]
	v_lshl_add_u64 v[102:103], v[104:105], 0, v[102:103]
	v_lshl_add_u64 v[128:129], s[22:23], 2, v[102:103]
	v_lshl_add_u64 v[102:103], v[128:129], 0, v[0:1]
	v_mov_b32_e32 v139, v1
	v_lshl_add_u64 v[114:115], v[102:103], 0, v[138:139]
	v_lshl_add_u64 v[240:241], v[114:115], 0, v[242:243]
	global_load_dwordx4 v[172:175], v[240:241], off
	global_load_dwordx4 v[176:179], v[240:241], off offset:64
	global_load_dwordx4 v[180:183], v[240:241], off offset:512
	global_load_dwordx4 v[184:187], v[240:241], off offset:576
	s_nop 0
	ds_read_b128 v[118:121], v140 offset:1024
	ds_read_b128 v[124:127], v140 offset:2048
	v_ashrrev_i32_e32 v101, 31, v100
	v_mov_b32_e32 v3, v1
	v_lshlrev_b64 v[130:131], 11, v[100:101]
	v_lshl_add_u64 v[130:131], s[18:19], 0, v[130:131]
	v_lshl_add_u64 v[128:129], v[128:129], 0, v[2:3]
	v_lshl_add_u64 v[142:143], v[132:133], 1, v[130:131]
	v_lshl_add_u64 v[130:131], v[134:135], 1, v[130:131]
	s_waitcnt vmcnt(4) lgkmcnt(0)
	v_mov_b64_e32 v[102:103], v[188:189]
	v_mov_b64_e32 v[104:105], v[190:191]
	v_mov_b64_e32 v[106:107], v[192:193]
	v_mov_b64_e32 v[108:109], v[194:195]
	v_mov_b64_e32 v[110:111], v[212:213]
	v_mov_b64_e32 v[112:113], v[214:215]
	v_mov_b64_e32 v[114:115], v[216:217]
	v_mov_b64_e32 v[116:117], v[218:219]
	v_pk_fma_f32 v[96:97], v[96:97], v[118:119], v[102:103]
	v_pk_fma_f32 v[98:99], v[98:99], v[120:121], v[104:105]
	v_pk_mul_f32 v[104:105], v[124:125], v[96:97]
	v_pk_mul_f32 v[120:121], v[126:127], v[98:99]
	v_pk_mul_f32 v[102:103], v[96:97], v[96:97]
	global_store_dwordx4 v[128:129], v[96:99], off
	v_pk_mul_f32 v[118:119], v[98:99], v[98:99]
	v_add_f32_e32 v3, v102, v103
	v_cvt_pk_bf16_f32 v96, v104, v105
	v_cvt_pk_bf16_f32 v97, v120, v121
	global_store_dwordx2 v[142:143], v[96:97], off
	ds_read_b128 v[96:99], v140 offset:1088
	ds_read_b128 v[102:105], v140 offset:2112
	v_add_f32_e32 v3, v118, v3
	v_add_f32_e32 v3, v119, v3
	s_waitcnt lgkmcnt(0)
	v_pk_fma_f32 v[88:89], v[88:89], v[96:97], v[106:107]
	v_pk_fma_f32 v[90:91], v[90:91], v[98:99], v[108:109]
	global_store_dwordx4 v[128:129], v[88:91], off offset:64
	v_pk_mul_f32 v[96:97], v[88:89], v[88:89]
	v_pk_mul_f32 v[106:107], v[90:91], v[90:91]
	v_pk_mul_f32 v[88:89], v[102:103], v[88:89]
	v_pk_mul_f32 v[90:91], v[104:105], v[90:91]
	v_cvt_pk_bf16_f32 v88, v88, v89
	v_cvt_pk_bf16_f32 v89, v90, v91
	global_store_dwordx2 v[130:131], v[88:89], off offset:32
	v_add_f32_e32 v96, v96, v97
	ds_read_b128 v[88:91], v140 offset:1536
	v_add_f32_e32 v102, v106, v96
	ds_read_b128 v[96:99], v140 offset:2560
	v_add_f32_e32 v102, v107, v102
	v_add_f32_e32 v3, v3, v102
	s_waitcnt lgkmcnt(0)
	v_pk_fma_f32 v[88:89], v[92:93], v[88:89], v[110:111]
	v_pk_fma_f32 v[90:91], v[94:95], v[90:91], v[112:113]
	global_store_dwordx4 v[128:129], v[88:91], off offset:512
	v_pk_mul_f32 v[92:93], v[88:89], v[88:89]
	v_pk_mul_f32 v[102:103], v[90:91], v[90:91]
	v_pk_mul_f32 v[88:89], v[96:97], v[88:89]
	v_pk_mul_f32 v[90:91], v[98:99], v[90:91]
	v_cvt_pk_bf16_f32 v88, v88, v89
	v_cvt_pk_bf16_f32 v89, v90, v91
	global_store_dwordx2 v[130:131], v[88:89], off offset:256
	ds_read_b128 v[88:91], v140 offset:1600
	v_add_f32_e32 v92, v92, v93
	v_add_f32_e32 v96, v102, v92
	ds_read_b128 v[92:95], v140 offset:2624
	v_add_f32_e32 v96, v103, v96
	s_waitcnt lgkmcnt(0)
	v_pk_fma_f32 v[84:85], v[84:85], v[88:89], v[114:115]
	v_pk_fma_f32 v[86:87], v[86:87], v[90:91], v[116:117]
	v_pk_mul_f32 v[88:89], v[84:85], v[84:85]
	v_pk_mul_f32 v[90:91], v[86:87], v[86:87]
	v_add_f32_e32 v88, v88, v89
	v_add_f32_e32 v88, v90, v88
	v_add_f32_e32 v3, v3, v96
	v_add_f32_e32 v88, v91, v88
	v_add_f32_e32 v3, v3, v88
	ds_bpermute_b32 v90, v122, v3
	global_store_dwordx4 v[128:129], v[84:87], off offset:576
	v_pk_mul_f32 v[88:89], v[92:93], v[84:85]
	s_waitcnt lgkmcnt(0)
	v_add_f32_e32 v3, v3, v90
	ds_bpermute_b32 v84, v123, v3
	v_pk_mul_f32 v[86:87], v[94:95], v[86:87]
	v_cvt_pk_bf16_f32 v88, v88, v89
	v_cvt_pk_bf16_f32 v89, v86, v87
	global_store_dwordx2 v[130:131], v[88:89], off offset:288
	s_and_saveexec_b64 s[26:27], s[6:7]
	s_cbranch_execz .LBB0_1470
	s_waitcnt lgkmcnt(0)
	v_add_f32_e32 v3, v3, v84
	v_lshl_add_u64 v[84:85], v[100:101], 2, s[20:21]
	global_atomic_add_f32 v[84:85], v3, off
.LBB0_1470:
	s_or_b64 exec, exec, s[26:27]
	s_waitcnt lgkmcnt(0)
	v_add_u32_e32 v84, 48, v136
	v_mul_hi_i32 v3, v84, s61
	v_lshrrev_b32_e32 v85, 31, v3
	v_ashrrev_i32_e32 v3, 11, v3
	v_add_u32_e32 v3, v3, v85
	v_mad_i32_i24 v85, v3, s48, v84
	v_cmp_lt_i32_e32 vcc, s49, v85
	s_and_saveexec_b64 s[26:27], vcc
	s_xor_b64 s[26:27], exec, s[26:27]
	v_lshlrev_b32_e32 v3, 12, v3
	s_movk_i32 s25, 0xff00
	v_add3_u32 v86, v3, v85, s25
	s_or_saveexec_b64 s[26:27], s[26:27]
	v_mov_b64_e32 v[88:89], s[12:13]
	s_xor_b64 exec, exec, s[26:27]
	v_lshl_add_u32 v86, v3, 8, v85
	v_mov_b64_e32 v[88:89], s[16:17]
	s_or_b64 exec, exec, s[26:27]
	v_ashrrev_i32_e32 v87, 31, v86
	v_lshlrev_b64 v[86:87], 12, v[86:87]
	v_lshl_add_u64 v[86:87], v[88:89], 0, v[86:87]
	v_lshl_add_u64 v[110:111], s[22:23], 2, v[86:87]
	v_lshl_add_u64 v[86:87], v[110:111], 0, v[0:1]
	v_mov_b32_e32 v139, v1
	v_lshl_add_u64 v[98:99], v[86:87], 0, v[138:139]
	v_lshl_add_u64 v[240:241], v[98:99], 0, v[244:245]
	global_load_dwordx4 v[188:191], v[240:241], off
	global_load_dwordx4 v[192:195], v[240:241], off offset:64
	global_load_dwordx4 v[212:215], v[240:241], off offset:512
	global_load_dwordx4 v[216:219], v[240:241], off offset:576
	s_nop 0
	ds_read_b128 v[102:105], v140 offset:1024
	ds_read_b128 v[106:109], v140 offset:2048
	v_ashrrev_i32_e32 v85, 31, v84
	v_mov_b32_e32 v3, v1
	v_lshlrev_b64 v[112:113], 11, v[84:85]
	v_lshl_add_u64 v[112:113], s[18:19], 0, v[112:113]
	v_lshl_add_u64 v[110:111], v[110:111], 0, v[2:3]
	v_lshl_add_u64 v[114:115], v[132:133], 1, v[112:113]
	v_lshl_add_u64 v[112:113], v[134:135], 1, v[112:113]
	s_waitcnt vmcnt(4) lgkmcnt(0)
	v_mov_b64_e32 v[86:87], v[172:173]
	v_mov_b64_e32 v[88:89], v[174:175]
	v_mov_b64_e32 v[90:91], v[176:177]
	v_mov_b64_e32 v[92:93], v[178:179]
	v_mov_b64_e32 v[94:95], v[180:181]
	v_mov_b64_e32 v[96:97], v[182:183]
	v_mov_b64_e32 v[98:99], v[184:185]
	v_mov_b64_e32 v[100:101], v[186:187]
	v_pk_fma_f32 v[80:81], v[80:81], v[102:103], v[86:87]
	v_pk_fma_f32 v[82:83], v[82:83], v[104:105], v[88:89]
	v_pk_mul_f32 v[88:89], v[106:107], v[80:81]
	v_pk_mul_f32 v[104:105], v[108:109], v[82:83]
	v_pk_mul_f32 v[86:87], v[80:81], v[80:81]
	global_store_dwordx4 v[110:111], v[80:83], off
	v_pk_mul_f32 v[102:103], v[82:83], v[82:83]
	v_add_f32_e32 v3, v86, v87
	v_cvt_pk_bf16_f32 v80, v88, v89
	v_cvt_pk_bf16_f32 v81, v104, v105
	global_store_dwordx2 v[114:115], v[80:81], off
	ds_read_b128 v[80:83], v140 offset:1088
	ds_read_b128 v[86:89], v140 offset:2112
	v_add_f32_e32 v3, v102, v3
	v_add_f32_e32 v3, v103, v3
	s_waitcnt lgkmcnt(0)
	v_pk_fma_f32 v[72:73], v[72:73], v[80:81], v[90:91]
	v_pk_fma_f32 v[74:75], v[74:75], v[82:83], v[92:93]
	global_store_dwordx4 v[110:111], v[72:75], off offset:64
	v_pk_mul_f32 v[80:81], v[72:73], v[72:73]
	v_pk_mul_f32 v[90:91], v[74:75], v[74:75]
	v_pk_mul_f32 v[72:73], v[86:87], v[72:73]
	v_pk_mul_f32 v[74:75], v[88:89], v[74:75]
	v_cvt_pk_bf16_f32 v72, v72, v73
	v_cvt_pk_bf16_f32 v73, v74, v75
	global_store_dwordx2 v[112:113], v[72:73], off offset:32
	v_add_f32_e32 v80, v80, v81
	ds_read_b128 v[72:75], v140 offset:1536
	v_add_f32_e32 v86, v90, v80
	ds_read_b128 v[80:83], v140 offset:2560
	v_add_f32_e32 v86, v91, v86
	v_add_f32_e32 v3, v3, v86
	s_waitcnt lgkmcnt(0)
	v_pk_fma_f32 v[72:73], v[76:77], v[72:73], v[94:95]
	v_pk_fma_f32 v[74:75], v[78:79], v[74:75], v[96:97]
	global_store_dwordx4 v[110:111], v[72:75], off offset:512
	v_pk_mul_f32 v[76:77], v[72:73], v[72:73]
	v_pk_mul_f32 v[86:87], v[74:75], v[74:75]
	v_pk_mul_f32 v[72:73], v[80:81], v[72:73]
	v_pk_mul_f32 v[74:75], v[82:83], v[74:75]
	v_cvt_pk_bf16_f32 v72, v72, v73
	v_cvt_pk_bf16_f32 v73, v74, v75
	global_store_dwordx2 v[112:113], v[72:73], off offset:256
	ds_read_b128 v[72:75], v140 offset:1600
	v_add_f32_e32 v76, v76, v77
	v_add_f32_e32 v80, v86, v76
	ds_read_b128 v[76:79], v140 offset:2624
	v_add_f32_e32 v80, v87, v80
	s_waitcnt lgkmcnt(0)
	v_pk_fma_f32 v[68:69], v[68:69], v[72:73], v[98:99]
	v_pk_fma_f32 v[70:71], v[70:71], v[74:75], v[100:101]
	v_pk_mul_f32 v[72:73], v[68:69], v[68:69]
	v_pk_mul_f32 v[74:75], v[70:71], v[70:71]
	v_add_f32_e32 v72, v72, v73
	v_add_f32_e32 v72, v74, v72
	v_add_f32_e32 v3, v3, v80
	v_add_f32_e32 v72, v75, v72
	v_add_f32_e32 v3, v3, v72
	ds_bpermute_b32 v74, v122, v3
	global_store_dwordx4 v[110:111], v[68:71], off offset:576
	v_pk_mul_f32 v[72:73], v[76:77], v[68:69]
	s_waitcnt lgkmcnt(0)
	v_add_f32_e32 v3, v3, v74
	ds_bpermute_b32 v68, v123, v3
	v_pk_mul_f32 v[70:71], v[78:79], v[70:71]
	v_cvt_pk_bf16_f32 v72, v72, v73
	v_cvt_pk_bf16_f32 v73, v70, v71
	global_store_dwordx2 v[112:113], v[72:73], off offset:288
	s_and_saveexec_b64 s[26:27], s[6:7]
	s_cbranch_execz .LBB0_1476
	s_waitcnt lgkmcnt(0)
	v_add_f32_e32 v3, v3, v68
	v_lshl_add_u64 v[68:69], v[84:85], 2, s[20:21]
	global_atomic_add_f32 v[68:69], v3, off
.LBB0_1476:
	s_or_b64 exec, exec, s[26:27]
	s_and_b64 vcc, exec, s[8:9]
	s_cbranch_vccnz .LBB0_1407
	s_waitcnt lgkmcnt(0)
	v_add_u32_e32 v68, 0x80, v136
	v_mul_hi_i32 v3, v68, s61
	v_lshrrev_b32_e32 v69, 31, v3
	v_ashrrev_i32_e32 v3, 11, v3
	v_add_u32_e32 v3, v3, v69
	v_mad_i32_i24 v69, v3, s48, v68
	v_cmp_lt_i32_e32 vcc, s49, v69
	s_and_saveexec_b64 s[8:9], vcc
	s_xor_b64 s[8:9], exec, s[8:9]
	v_lshlrev_b32_e32 v3, 12, v3
	s_movk_i32 s25, 0xff00
	v_add3_u32 v70, v3, v69, s25
	s_or_saveexec_b64 s[8:9], s[8:9]
	v_mov_b64_e32 v[72:73], s[12:13]
	s_xor_b64 exec, exec, s[8:9]
	v_lshl_add_u32 v70, v3, 8, v69
	v_mov_b64_e32 v[72:73], s[16:17]
	s_or_b64 exec, exec, s[8:9]
	v_ashrrev_i32_e32 v71, 31, v70
	v_lshlrev_b64 v[70:71], 12, v[70:71]
	v_lshl_add_u64 v[70:71], v[72:73], 0, v[70:71]
	v_lshl_add_u64 v[94:95], s[22:23], 2, v[70:71]
	v_lshl_add_u64 v[70:71], v[94:95], 0, v[0:1]
	v_mov_b32_e32 v139, v1
	v_lshl_add_u64 v[82:83], v[70:71], 0, v[138:139]
	v_lshl_add_u64 v[240:241], v[82:83], 0, v[242:243]
	global_load_dwordx4 v[172:175], v[240:241], off
	global_load_dwordx4 v[176:179], v[240:241], off offset:64
	global_load_dwordx4 v[180:183], v[240:241], off offset:512
	global_load_dwordx4 v[184:187], v[240:241], off offset:576
	s_nop 0
	ds_read_b128 v[86:89], v140 offset:1024
	ds_read_b128 v[90:93], v140 offset:2048
	v_ashrrev_i32_e32 v69, 31, v68
	v_mov_b32_e32 v3, v1
	v_lshlrev_b64 v[96:97], 11, v[68:69]
	v_lshl_add_u64 v[96:97], s[18:19], 0, v[96:97]
	v_lshl_add_u64 v[94:95], v[94:95], 0, v[2:3]
	v_lshl_add_u64 v[98:99], v[132:133], 1, v[96:97]
	v_lshl_add_u64 v[96:97], v[134:135], 1, v[96:97]
	s_waitcnt vmcnt(4) lgkmcnt(0)
	v_mov_b64_e32 v[70:71], v[188:189]
	v_mov_b64_e32 v[72:73], v[190:191]
	v_mov_b64_e32 v[74:75], v[192:193]
	v_mov_b64_e32 v[76:77], v[194:195]
	v_mov_b64_e32 v[78:79], v[212:213]
	v_mov_b64_e32 v[80:81], v[214:215]
	v_mov_b64_e32 v[82:83], v[216:217]
	v_mov_b64_e32 v[84:85], v[218:219]
	v_pk_fma_f32 v[64:65], v[64:65], v[86:87], v[70:71]
	v_pk_fma_f32 v[66:67], v[66:67], v[88:89], v[72:73]
	v_pk_mul_f32 v[72:73], v[90:91], v[64:65]
	v_pk_mul_f32 v[88:89], v[92:93], v[66:67]
	v_pk_mul_f32 v[70:71], v[64:65], v[64:65]
	global_store_dwordx4 v[94:95], v[64:67], off
	v_pk_mul_f32 v[86:87], v[66:67], v[66:67]
	v_add_f32_e32 v3, v70, v71
	v_cvt_pk_bf16_f32 v64, v72, v73
	v_cvt_pk_bf16_f32 v65, v88, v89
	global_store_dwordx2 v[98:99], v[64:65], off
	ds_read_b128 v[64:67], v140 offset:1088
	ds_read_b128 v[70:73], v140 offset:2112
	v_add_f32_e32 v3, v86, v3
	v_add_f32_e32 v3, v87, v3
	s_waitcnt lgkmcnt(0)
	v_pk_fma_f32 v[60:61], v[60:61], v[64:65], v[74:75]
	v_pk_fma_f32 v[62:63], v[62:63], v[66:67], v[76:77]
	global_store_dwordx4 v[94:95], v[60:63], off offset:64
	v_pk_mul_f32 v[64:65], v[60:61], v[60:61]
	v_pk_mul_f32 v[74:75], v[62:63], v[62:63]
	v_pk_mul_f32 v[60:61], v[70:71], v[60:61]
	v_pk_mul_f32 v[62:63], v[72:73], v[62:63]
	v_cvt_pk_bf16_f32 v60, v60, v61
	v_cvt_pk_bf16_f32 v61, v62, v63
	global_store_dwordx2 v[96:97], v[60:61], off offset:32
	v_add_f32_e32 v64, v64, v65
	ds_read_b128 v[60:63], v140 offset:1536
	v_add_f32_e32 v70, v74, v64
	ds_read_b128 v[64:67], v140 offset:2560
	v_add_f32_e32 v70, v75, v70
	v_add_f32_e32 v3, v3, v70
	s_waitcnt lgkmcnt(0)
	v_pk_fma_f32 v[56:57], v[56:57], v[60:61], v[78:79]
	v_pk_fma_f32 v[58:59], v[58:59], v[62:63], v[80:81]
	global_store_dwordx4 v[94:95], v[56:59], off offset:512
	v_pk_mul_f32 v[60:61], v[56:57], v[56:57]
	v_pk_mul_f32 v[70:71], v[58:59], v[58:59]
	v_pk_mul_f32 v[56:57], v[64:65], v[56:57]
	v_pk_mul_f32 v[58:59], v[66:67], v[58:59]
	v_cvt_pk_bf16_f32 v56, v56, v57
	v_cvt_pk_bf16_f32 v57, v58, v59
	global_store_dwordx2 v[96:97], v[56:57], off offset:256
	ds_read_b128 v[56:59], v140 offset:1600
	v_add_f32_e32 v60, v60, v61
	v_add_f32_e32 v64, v70, v60
	ds_read_b128 v[60:63], v140 offset:2624
	v_add_f32_e32 v64, v71, v64
	s_waitcnt lgkmcnt(0)
	v_pk_fma_f32 v[52:53], v[52:53], v[56:57], v[82:83]
	v_pk_fma_f32 v[54:55], v[54:55], v[58:59], v[84:85]
	v_pk_mul_f32 v[56:57], v[52:53], v[52:53]
	v_pk_mul_f32 v[58:59], v[54:55], v[54:55]
	v_add_f32_e32 v56, v56, v57
	v_add_f32_e32 v56, v58, v56
	v_add_f32_e32 v3, v3, v64
	v_add_f32_e32 v56, v59, v56
	v_add_f32_e32 v3, v3, v56
	ds_bpermute_b32 v58, v122, v3
	global_store_dwordx4 v[94:95], v[52:55], off offset:576
	v_pk_mul_f32 v[56:57], v[60:61], v[52:53]
	s_waitcnt lgkmcnt(0)
	v_add_f32_e32 v3, v3, v58
	ds_bpermute_b32 v52, v123, v3
	v_pk_mul_f32 v[54:55], v[62:63], v[54:55]
	v_cvt_pk_bf16_f32 v56, v56, v57
	v_cvt_pk_bf16_f32 v57, v54, v55
	global_store_dwordx2 v[96:97], v[56:57], off offset:288
	s_and_saveexec_b64 s[8:9], s[6:7]
	s_cbranch_execz .LBB0_1483
	s_waitcnt lgkmcnt(0)
	v_add_f32_e32 v3, v3, v52
	v_lshl_add_u64 v[52:53], v[68:69], 2, s[20:21]
	global_atomic_add_f32 v[52:53], v3, off
.LBB0_1483:
	s_or_b64 exec, exec, s[8:9]
	s_waitcnt lgkmcnt(0)
	v_add_u32_e32 v52, 0x90, v136
	v_mul_hi_i32 v3, v52, s61
	v_lshrrev_b32_e32 v53, 31, v3
	v_ashrrev_i32_e32 v3, 11, v3
	v_add_u32_e32 v3, v3, v53
	v_mad_i32_i24 v53, v3, s48, v52
	v_cmp_lt_i32_e32 vcc, s49, v53
	s_and_saveexec_b64 s[8:9], vcc
	s_xor_b64 s[8:9], exec, s[8:9]
	v_lshlrev_b32_e32 v3, 12, v3
	s_movk_i32 s25, 0xff00
	v_add3_u32 v54, v3, v53, s25
	s_or_saveexec_b64 s[8:9], s[8:9]
	v_mov_b64_e32 v[56:57], s[12:13]
	s_xor_b64 exec, exec, s[8:9]
	v_lshl_add_u32 v54, v3, 8, v53
	v_mov_b64_e32 v[56:57], s[16:17]
	s_or_b64 exec, exec, s[8:9]
	v_ashrrev_i32_e32 v55, 31, v54
	v_lshlrev_b64 v[54:55], 12, v[54:55]
	v_lshl_add_u64 v[54:55], v[56:57], 0, v[54:55]
	v_lshl_add_u64 v[78:79], s[22:23], 2, v[54:55]
	v_lshl_add_u64 v[54:55], v[78:79], 0, v[0:1]
	v_mov_b32_e32 v139, v1
	v_lshl_add_u64 v[66:67], v[54:55], 0, v[138:139]
	v_lshl_add_u64 v[240:241], v[66:67], 0, v[242:243]
	global_load_dwordx4 v[188:191], v[240:241], off
	global_load_dwordx4 v[192:195], v[240:241], off offset:64
	global_load_dwordx4 v[212:215], v[240:241], off offset:512
	global_load_dwordx4 v[216:219], v[240:241], off offset:576
	s_nop 0
	ds_read_b128 v[70:73], v140 offset:1024
	ds_read_b128 v[74:77], v140 offset:2048
	v_ashrrev_i32_e32 v53, 31, v52
	v_mov_b32_e32 v3, v1
	v_lshlrev_b64 v[80:81], 11, v[52:53]
	v_lshl_add_u64 v[80:81], s[18:19], 0, v[80:81]
	v_lshl_add_u64 v[78:79], v[78:79], 0, v[2:3]
	v_lshl_add_u64 v[82:83], v[132:133], 1, v[80:81]
	v_lshl_add_u64 v[80:81], v[134:135], 1, v[80:81]
	s_waitcnt vmcnt(4) lgkmcnt(0)
	v_mov_b64_e32 v[54:55], v[172:173]
	v_mov_b64_e32 v[56:57], v[174:175]
	v_mov_b64_e32 v[58:59], v[176:177]
	v_mov_b64_e32 v[60:61], v[178:179]
	v_mov_b64_e32 v[62:63], v[180:181]
	v_mov_b64_e32 v[64:65], v[182:183]
	v_mov_b64_e32 v[66:67], v[184:185]
	v_mov_b64_e32 v[68:69], v[186:187]
	v_pk_fma_f32 v[48:49], v[48:49], v[70:71], v[54:55]
	v_pk_fma_f32 v[50:51], v[50:51], v[72:73], v[56:57]
	v_pk_mul_f32 v[56:57], v[74:75], v[48:49]
	v_pk_mul_f32 v[72:73], v[76:77], v[50:51]
	v_pk_mul_f32 v[54:55], v[48:49], v[48:49]
	global_store_dwordx4 v[78:79], v[48:51], off
	v_pk_mul_f32 v[70:71], v[50:51], v[50:51]
	v_add_f32_e32 v3, v54, v55
	v_cvt_pk_bf16_f32 v48, v56, v57
	v_cvt_pk_bf16_f32 v49, v72, v73
	global_store_dwordx2 v[82:83], v[48:49], off
	ds_read_b128 v[48:51], v140 offset:1088
	ds_read_b128 v[54:57], v140 offset:2112
	v_add_f32_e32 v3, v70, v3
	v_add_f32_e32 v3, v71, v3
	s_waitcnt lgkmcnt(0)
	v_pk_fma_f32 v[44:45], v[44:45], v[48:49], v[58:59]
	v_pk_fma_f32 v[46:47], v[46:47], v[50:51], v[60:61]
	global_store_dwordx4 v[78:79], v[44:47], off offset:64
	v_pk_mul_f32 v[48:49], v[44:45], v[44:45]
	v_pk_mul_f32 v[58:59], v[46:47], v[46:47]
	v_pk_mul_f32 v[44:45], v[54:55], v[44:45]
	v_pk_mul_f32 v[46:47], v[56:57], v[46:47]
	v_cvt_pk_bf16_f32 v44, v44, v45
	v_cvt_pk_bf16_f32 v45, v46, v47
	global_store_dwordx2 v[80:81], v[44:45], off offset:32
	v_add_f32_e32 v48, v48, v49
	ds_read_b128 v[44:47], v140 offset:1536
	v_add_f32_e32 v54, v58, v48
	ds_read_b128 v[48:51], v140 offset:2560
	v_add_f32_e32 v54, v59, v54
	v_add_f32_e32 v3, v3, v54
	s_waitcnt lgkmcnt(0)
	v_pk_fma_f32 v[40:41], v[40:41], v[44:45], v[62:63]
	v_pk_fma_f32 v[42:43], v[42:43], v[46:47], v[64:65]
	global_store_dwordx4 v[78:79], v[40:43], off offset:512
	v_pk_mul_f32 v[44:45], v[40:41], v[40:41]
	v_pk_mul_f32 v[54:55], v[42:43], v[42:43]
	v_pk_mul_f32 v[40:41], v[48:49], v[40:41]
	v_pk_mul_f32 v[42:43], v[50:51], v[42:43]
	v_cvt_pk_bf16_f32 v40, v40, v41
	v_cvt_pk_bf16_f32 v41, v42, v43
	global_store_dwordx2 v[80:81], v[40:41], off offset:256
	ds_read_b128 v[40:43], v140 offset:1600
	v_add_f32_e32 v44, v44, v45
	v_add_f32_e32 v48, v54, v44
	ds_read_b128 v[44:47], v140 offset:2624
	v_add_f32_e32 v48, v55, v48
	s_waitcnt lgkmcnt(0)
	v_pk_fma_f32 v[36:37], v[36:37], v[40:41], v[66:67]
	v_pk_fma_f32 v[38:39], v[38:39], v[42:43], v[68:69]
	v_pk_mul_f32 v[40:41], v[36:37], v[36:37]
	v_pk_mul_f32 v[42:43], v[38:39], v[38:39]
	v_add_f32_e32 v40, v40, v41
	v_add_f32_e32 v40, v42, v40
	v_add_f32_e32 v3, v3, v48
	v_add_f32_e32 v40, v43, v40
	v_add_f32_e32 v3, v3, v40
	ds_bpermute_b32 v42, v122, v3
	global_store_dwordx4 v[78:79], v[36:39], off offset:576
	v_pk_mul_f32 v[40:41], v[44:45], v[36:37]
	s_waitcnt lgkmcnt(0)
	v_add_f32_e32 v3, v3, v42
	ds_bpermute_b32 v36, v123, v3
	v_pk_mul_f32 v[38:39], v[46:47], v[38:39]
	v_cvt_pk_bf16_f32 v40, v40, v41
	v_cvt_pk_bf16_f32 v41, v38, v39
	global_store_dwordx2 v[80:81], v[40:41], off offset:288
	s_and_saveexec_b64 s[8:9], s[6:7]
	s_cbranch_execz .LBB0_1489
	s_waitcnt lgkmcnt(0)
	v_add_f32_e32 v3, v3, v36
	v_lshl_add_u64 v[36:37], v[52:53], 2, s[20:21]
	global_atomic_add_f32 v[36:37], v3, off
.LBB0_1489:
	s_or_b64 exec, exec, s[8:9]
	s_waitcnt lgkmcnt(0)
	v_add_u32_e32 v36, 0xa0, v136
	v_mul_hi_i32 v3, v36, s61
	v_lshrrev_b32_e32 v37, 31, v3
	v_ashrrev_i32_e32 v3, 11, v3
	v_add_u32_e32 v3, v3, v37
	v_mad_i32_i24 v37, v3, s48, v36
	v_cmp_lt_i32_e32 vcc, s49, v37
	s_and_saveexec_b64 s[8:9], vcc
	s_xor_b64 s[8:9], exec, s[8:9]
	v_lshlrev_b32_e32 v3, 12, v3
	s_movk_i32 s25, 0xff00
	v_add3_u32 v38, v3, v37, s25
	s_or_saveexec_b64 s[8:9], s[8:9]
	v_mov_b64_e32 v[40:41], s[12:13]
	s_xor_b64 exec, exec, s[8:9]
	v_lshl_add_u32 v38, v3, 8, v37
	v_mov_b64_e32 v[40:41], s[16:17]
	s_or_b64 exec, exec, s[8:9]
	v_ashrrev_i32_e32 v39, 31, v38
	v_lshlrev_b64 v[38:39], 12, v[38:39]
	v_lshl_add_u64 v[38:39], v[40:41], 0, v[38:39]
	v_lshl_add_u64 v[62:63], s[22:23], 2, v[38:39]
	v_lshl_add_u64 v[38:39], v[62:63], 0, v[0:1]
	v_mov_b32_e32 v139, v1
	v_lshl_add_u64 v[50:51], v[38:39], 0, v[138:139]
	v_lshl_add_u64 v[240:241], v[50:51], 0, v[242:243]
	global_load_dwordx4 v[172:175], v[240:241], off
	global_load_dwordx4 v[176:179], v[240:241], off offset:64
	global_load_dwordx4 v[180:183], v[240:241], off offset:512
	global_load_dwordx4 v[184:187], v[240:241], off offset:576
	s_nop 0
	ds_read_b128 v[54:57], v140 offset:1024
	ds_read_b128 v[58:61], v140 offset:2048
	v_ashrrev_i32_e32 v37, 31, v36
	v_mov_b32_e32 v3, v1
	v_lshlrev_b64 v[64:65], 11, v[36:37]
	v_lshl_add_u64 v[64:65], s[18:19], 0, v[64:65]
	v_lshl_add_u64 v[62:63], v[62:63], 0, v[2:3]
	v_lshl_add_u64 v[66:67], v[132:133], 1, v[64:65]
	v_lshl_add_u64 v[64:65], v[134:135], 1, v[64:65]
	s_waitcnt vmcnt(4) lgkmcnt(0)
	v_mov_b64_e32 v[38:39], v[188:189]
	v_mov_b64_e32 v[40:41], v[190:191]
	v_mov_b64_e32 v[42:43], v[192:193]
	v_mov_b64_e32 v[44:45], v[194:195]
	v_mov_b64_e32 v[46:47], v[212:213]
	v_mov_b64_e32 v[48:49], v[214:215]
	v_mov_b64_e32 v[50:51], v[216:217]
	v_mov_b64_e32 v[52:53], v[218:219]
	v_pk_fma_f32 v[32:33], v[32:33], v[54:55], v[38:39]
	v_pk_fma_f32 v[34:35], v[34:35], v[56:57], v[40:41]
	v_pk_mul_f32 v[40:41], v[58:59], v[32:33]
	v_pk_mul_f32 v[56:57], v[60:61], v[34:35]
	v_pk_mul_f32 v[38:39], v[32:33], v[32:33]
	global_store_dwordx4 v[62:63], v[32:35], off
	v_pk_mul_f32 v[54:55], v[34:35], v[34:35]
	v_add_f32_e32 v3, v38, v39
	v_cvt_pk_bf16_f32 v32, v40, v41
	v_cvt_pk_bf16_f32 v33, v56, v57
	global_store_dwordx2 v[66:67], v[32:33], off
	ds_read_b128 v[32:35], v140 offset:1088
	ds_read_b128 v[38:41], v140 offset:2112
	v_add_f32_e32 v3, v54, v3
	v_add_f32_e32 v3, v55, v3
	s_waitcnt lgkmcnt(0)
	v_pk_fma_f32 v[28:29], v[28:29], v[32:33], v[42:43]
	v_pk_fma_f32 v[30:31], v[30:31], v[34:35], v[44:45]
	global_store_dwordx4 v[62:63], v[28:31], off offset:64
	v_pk_mul_f32 v[32:33], v[28:29], v[28:29]
	v_pk_mul_f32 v[42:43], v[30:31], v[30:31]
	v_pk_mul_f32 v[28:29], v[38:39], v[28:29]
	v_pk_mul_f32 v[30:31], v[40:41], v[30:31]
	v_cvt_pk_bf16_f32 v28, v28, v29
	v_cvt_pk_bf16_f32 v29, v30, v31
	global_store_dwordx2 v[64:65], v[28:29], off offset:32
	v_add_f32_e32 v32, v32, v33
	ds_read_b128 v[28:31], v140 offset:1536
	v_add_f32_e32 v38, v42, v32
	ds_read_b128 v[32:35], v140 offset:2560
	v_add_f32_e32 v38, v43, v38
	v_add_f32_e32 v3, v3, v38
	s_waitcnt lgkmcnt(0)
	v_pk_fma_f32 v[24:25], v[24:25], v[28:29], v[46:47]
	v_pk_fma_f32 v[26:27], v[26:27], v[30:31], v[48:49]
	global_store_dwordx4 v[62:63], v[24:27], off offset:512
	v_pk_mul_f32 v[28:29], v[24:25], v[24:25]
	v_pk_mul_f32 v[38:39], v[26:27], v[26:27]
	v_pk_mul_f32 v[24:25], v[32:33], v[24:25]
	v_pk_mul_f32 v[26:27], v[34:35], v[26:27]
	v_cvt_pk_bf16_f32 v24, v24, v25
	v_cvt_pk_bf16_f32 v25, v26, v27
	global_store_dwordx2 v[64:65], v[24:25], off offset:256
	ds_read_b128 v[24:27], v140 offset:1600
	v_add_f32_e32 v28, v28, v29
	v_add_f32_e32 v32, v38, v28
	ds_read_b128 v[28:31], v140 offset:2624
	v_add_f32_e32 v32, v39, v32
	s_waitcnt lgkmcnt(0)
	v_pk_fma_f32 v[20:21], v[20:21], v[24:25], v[50:51]
	v_pk_fma_f32 v[22:23], v[22:23], v[26:27], v[52:53]
	v_pk_mul_f32 v[24:25], v[20:21], v[20:21]
	v_pk_mul_f32 v[26:27], v[22:23], v[22:23]
	v_add_f32_e32 v24, v24, v25
	v_add_f32_e32 v24, v26, v24
	v_add_f32_e32 v3, v3, v32
	v_add_f32_e32 v24, v27, v24
	v_add_f32_e32 v3, v3, v24
	ds_bpermute_b32 v26, v122, v3
	global_store_dwordx4 v[62:63], v[20:23], off offset:576
	v_pk_mul_f32 v[24:25], v[28:29], v[20:21]
	s_waitcnt lgkmcnt(0)
	v_add_f32_e32 v3, v3, v26
	ds_bpermute_b32 v20, v123, v3
	v_pk_mul_f32 v[22:23], v[30:31], v[22:23]
	v_cvt_pk_bf16_f32 v24, v24, v25
	v_cvt_pk_bf16_f32 v25, v22, v23
	global_store_dwordx2 v[64:65], v[24:25], off offset:288
	s_and_saveexec_b64 s[8:9], s[6:7]
	s_cbranch_execz .LBB0_1495
	s_waitcnt lgkmcnt(0)
	v_add_f32_e32 v3, v3, v20
	v_lshl_add_u64 v[20:21], v[36:37], 2, s[20:21]
	global_atomic_add_f32 v[20:21], v3, off
.LBB0_1495:
	s_or_b64 exec, exec, s[8:9]
	s_waitcnt lgkmcnt(0)
	v_add_u32_e32 v20, 0xb0, v136
	v_mul_hi_i32 v3, v20, s61
	v_lshrrev_b32_e32 v21, 31, v3
	v_ashrrev_i32_e32 v3, 11, v3
	v_add_u32_e32 v3, v3, v21
	v_mad_i32_i24 v21, v3, s48, v20
	v_cmp_lt_i32_e32 vcc, s49, v21
	s_and_saveexec_b64 s[8:9], vcc
	s_xor_b64 s[8:9], exec, s[8:9]
	v_lshlrev_b32_e32 v3, 12, v3
	s_movk_i32 s25, 0xff00
	v_add3_u32 v22, v3, v21, s25
	s_or_saveexec_b64 s[8:9], s[8:9]
	v_mov_b64_e32 v[24:25], s[12:13]
	s_xor_b64 exec, exec, s[8:9]
	v_lshl_add_u32 v22, v3, 8, v21
	v_mov_b64_e32 v[24:25], s[16:17]
	s_or_b64 exec, exec, s[8:9]
	v_ashrrev_i32_e32 v23, 31, v22
	v_lshlrev_b64 v[22:23], 12, v[22:23]
	v_lshl_add_u64 v[22:23], v[24:25], 0, v[22:23]
	v_lshl_add_u64 v[46:47], s[22:23], 2, v[22:23]
	v_lshl_add_u64 v[22:23], v[46:47], 0, v[0:1]
	v_mov_b32_e32 v139, v1
	v_lshl_add_u64 v[34:35], v[22:23], 0, v[138:139]
	s_nop 0
	ds_read_b128 v[38:41], v140 offset:1024
	ds_read_b128 v[42:45], v140 offset:2048
	v_ashrrev_i32_e32 v21, 31, v20
	v_mov_b32_e32 v3, v1
	v_lshlrev_b64 v[48:49], 11, v[20:21]
	v_lshl_add_u64 v[48:49], s[18:19], 0, v[48:49]
	v_lshl_add_u64 v[46:47], v[46:47], 0, v[2:3]
	v_lshl_add_u64 v[50:51], v[132:133], 1, v[48:49]
	v_lshl_add_u64 v[48:49], v[134:135], 1, v[48:49]
	s_waitcnt vmcnt(0) lgkmcnt(0)
	v_mov_b64_e32 v[22:23], v[172:173]
	v_mov_b64_e32 v[24:25], v[174:175]
	v_mov_b64_e32 v[26:27], v[176:177]
	v_mov_b64_e32 v[28:29], v[178:179]
	v_mov_b64_e32 v[30:31], v[180:181]
	v_mov_b64_e32 v[32:33], v[182:183]
	v_mov_b64_e32 v[34:35], v[184:185]
	v_mov_b64_e32 v[36:37], v[186:187]
	v_pk_fma_f32 v[16:17], v[16:17], v[38:39], v[22:23]
	v_pk_fma_f32 v[18:19], v[18:19], v[40:41], v[24:25]
	v_pk_mul_f32 v[22:23], v[42:43], v[16:17]
	v_pk_mul_f32 v[24:25], v[44:45], v[18:19]
	v_pk_mul_f32 v[2:3], v[16:17], v[16:17]
	global_store_dwordx4 v[46:47], v[16:19], off
	v_pk_mul_f32 v[38:39], v[18:19], v[18:19]
	v_add_f32_e32 v0, v2, v3
	v_cvt_pk_bf16_f32 v16, v22, v23
	v_cvt_pk_bf16_f32 v17, v24, v25
	global_store_dwordx2 v[50:51], v[16:17], off
	ds_read_b128 v[16:19], v140 offset:1088
	ds_read_b128 v[22:25], v140 offset:2112
	v_add_f32_e32 v0, v38, v0
	v_add_f32_e32 v0, v39, v0
	s_waitcnt lgkmcnt(0)
	v_pk_fma_f32 v[12:13], v[12:13], v[16:17], v[26:27]
	v_pk_fma_f32 v[14:15], v[14:15], v[18:19], v[28:29]
	global_store_dwordx4 v[46:47], v[12:15], off offset:64
	v_pk_mul_f32 v[2:3], v[12:13], v[12:13]
	v_pk_mul_f32 v[26:27], v[14:15], v[14:15]
	v_pk_mul_f32 v[12:13], v[22:23], v[12:13]
	v_pk_mul_f32 v[14:15], v[24:25], v[14:15]
	v_cvt_pk_bf16_f32 v12, v12, v13
	v_cvt_pk_bf16_f32 v13, v14, v15
	global_store_dwordx2 v[48:49], v[12:13], off offset:32
	ds_read_b128 v[12:15], v140 offset:1536
	ds_read_b128 v[16:19], v140 offset:2560
	v_add_f32_e32 v2, v2, v3
	v_add_f32_e32 v2, v26, v2
	v_add_f32_e32 v2, v27, v2
	s_waitcnt lgkmcnt(0)
	v_pk_fma_f32 v[8:9], v[8:9], v[12:13], v[30:31]
	v_pk_fma_f32 v[10:11], v[10:11], v[14:15], v[32:33]
	v_add_f32_e32 v0, v0, v2
	global_store_dwordx4 v[46:47], v[8:11], off offset:512
	v_pk_mul_f32 v[2:3], v[8:9], v[8:9]
	v_pk_mul_f32 v[22:23], v[10:11], v[10:11]
	v_pk_mul_f32 v[8:9], v[16:17], v[8:9]
	v_pk_mul_f32 v[10:11], v[18:19], v[10:11]
	v_cvt_pk_bf16_f32 v8, v8, v9
	v_cvt_pk_bf16_f32 v9, v10, v11
	global_store_dwordx2 v[48:49], v[8:9], off offset:256
	ds_read_b128 v[8:11], v140 offset:1600
	ds_read_b128 v[12:15], v140 offset:2624
	v_add_f32_e32 v2, v2, v3
	v_add_f32_e32 v2, v22, v2
	v_add_f32_e32 v16, v23, v2
	s_waitcnt lgkmcnt(0)
	v_pk_fma_f32 v[2:3], v[4:5], v[8:9], v[34:35]
	v_pk_fma_f32 v[4:5], v[6:7], v[10:11], v[36:37]
	v_pk_mul_f32 v[6:7], v[2:3], v[2:3]
	v_pk_mul_f32 v[8:9], v[4:5], v[4:5]
	v_add_f32_e32 v6, v6, v7
	v_add_f32_e32 v6, v8, v6
	v_add_f32_e32 v0, v0, v16
	v_add_f32_e32 v6, v9, v6
	v_add_f32_e32 v0, v0, v6
	ds_bpermute_b32 v8, v122, v0
	global_store_dwordx4 v[46:47], v[2:5], off offset:576
	v_pk_mul_f32 v[6:7], v[12:13], v[2:3]
	s_waitcnt lgkmcnt(0)
	v_add_f32_e32 v0, v0, v8
	ds_bpermute_b32 v2, v123, v0
	v_pk_mul_f32 v[4:5], v[14:15], v[4:5]
	v_cvt_pk_bf16_f32 v6, v6, v7
	v_cvt_pk_bf16_f32 v7, v4, v5
	global_store_dwordx2 v[48:49], v[6:7], off offset:288
	s_and_saveexec_b64 s[8:9], s[6:7]
	s_cbranch_execz .LBB0_1406
	s_waitcnt lgkmcnt(0)
	v_add_f32_e32 v0, v0, v2
	v_lshl_add_u64 v[2:3], v[20:21], 2, s[20:21]
	global_atomic_add_f32 v[2:3], v0, off
	s_branch .LBB0_1406

.LBB0_1656:
	s_or_b64 exec, exec, s[8:9]
	v_add_u32_e32 v150, s56, v229
	v_mul_hi_i32 v0, v150, s61
	v_lshrrev_b32_e32 v2, 31, v0
	v_ashrrev_i32_e32 v0, 11, v0
	v_add_u32_e32 v0, v0, v2
	v_mad_i32_i24 v3, v0, s48, v150
	v_cmp_lt_i32_e32 vcc, s49, v3
	s_and_saveexec_b64 s[8:9], vcc
	s_xor_b64 s[8:9], exec, s[8:9]
	v_lshlrev_b32_e32 v0, 12, v0
	s_movk_i32 s26, 0xff00
	v_add3_u32 v2, v0, v3, s26
	s_or_saveexec_b64 s[8:9], s[8:9]
	s_waitcnt lgkmcnt(0)
	v_mov_b64_e32 v[132:133], s[14:15]
	s_xor_b64 exec, exec, s[8:9]
	v_lshl_add_u32 v2, v0, 8, v3
	v_mov_b64_e32 v[132:133], s[18:19]
	s_or_b64 exec, exec, s[8:9]
	v_ashrrev_i32_e32 v3, 31, v2
	v_lshlrev_b64 v[2:3], 12, v[2:3]
	v_lshl_add_u64 v[2:3], v[132:133], 0, v[2:3]
	v_lshl_add_u64 v[164:165], s[24:25], 2, v[2:3]
	v_lshlrev_b32_e32 v0, 2, v200
	v_ashrrev_i32_e32 v151, 31, v150
	v_lshl_add_u64 v[2:3], v[164:165], 0, v[0:1]
	v_lshlrev_b32_e32 v152, 2, v202
	v_mov_b32_e32 v153, v1
	v_lshlrev_b32_e32 v148, 2, v204
	v_lshlrev_b64 v[144:145], 11, v[150:151]
	v_lshl_add_u64 v[160:161], v[2:3], 0, v[152:153]
	v_add_u32_e32 v158, s58, v148
	s_waitcnt vmcnt(0)
	v_mov_b32_e32 v242, 0x10000
	v_mov_b32_e32 v243, 0
	v_mov_b32_e32 v244, 0x50000
	v_mov_b32_e32 v245, 0
	v_lshl_add_u64 v[240:241], v[160:161], 0, v[242:243]
	global_load_dwordx4 v[140:143], v[160:161], off offset:64
	global_load_dwordx4 v[136:139], v[160:161], off offset:512
	global_load_dwordx4 v[132:135], v[160:161], off offset:576
	v_lshl_add_u64 v[166:167], s[20:21], 0, v[144:145]
	ds_read_b128 v[154:157], v158 offset:1024
	ds_read_b128 v[144:147], v158 offset:2048
	global_load_dwordx4 v[160:163], v[160:161], off
	global_load_dwordx4 v[172:175], v[240:241], off
	global_load_dwordx4 v[176:179], v[240:241], off offset:64
	global_load_dwordx4 v[180:183], v[240:241], off offset:512
	global_load_dwordx4 v[184:187], v[240:241], off offset:576
	v_add_u32_e32 v2, s24, v204
	v_ashrrev_i32_e32 v3, 31, v2
	v_mov_b32_e32 v149, v1
	v_cndmask_b32_e64 v153, 0, 1, s[92:93]
	v_cmp_ne_u32_e64 s[8:9], 1, v153
	s_andn2_b64 vcc, exec, s[92:93]
	s_waitcnt vmcnt(4) lgkmcnt(0)
	v_pk_fma_f32 v[128:129], v[128:129], v[154:155], v[160:161]
	v_pk_fma_f32 v[130:131], v[130:131], v[156:157], v[162:163]
	v_lshl_add_u64 v[154:155], v[164:165], 0, v[148:149]
	v_mov_b32_e32 v149, 0
	v_lshl_add_u64 v[156:157], v[2:3], 1, v[166:167]
	global_store_dwordx4 v[154:155], v[128:131], off
	s_cbranch_vccnz .LBB0_1662
	v_pk_mul_f32 v[160:161], v[128:129], v[128:129]
	v_pk_mul_f32 v[162:163], v[130:131], v[130:131]
	v_add_f32_e32 v149, v160, v161
	v_add_f32_e32 v149, v162, v149
	v_pk_mul_f32 v[128:129], v[144:145], v[128:129]
	v_pk_mul_f32 v[130:131], v[146:147], v[130:131]
	v_add_f32_e32 v149, v163, v149
	v_cvt_pk_bf16_f32 v128, v128, v129
	v_cvt_pk_bf16_f32 v129, v130, v131
	global_store_dwordx2 v[156:157], v[128:129], off

.LBB0_1670:
	v_add_u32_e32 v132, 16, v150
	v_mul_hi_i32 v116, v132, s61
	s_waitcnt lgkmcnt(0)
	v_lshrrev_b32_e32 v117, 31, v116
	v_ashrrev_i32_e32 v116, 11, v116
	v_add_u32_e32 v117, v116, v117
	v_mad_i32_i24 v120, v117, s48, v132
	v_cmp_lt_i32_e32 vcc, s49, v120
	s_and_saveexec_b64 s[26:27], vcc
	s_xor_b64 s[26:27], exec, s[26:27]
	v_lshlrev_b32_e32 v116, 12, v117
	s_movk_i32 s28, 0xff00
	v_add3_u32 v116, v116, v120, s28
	s_or_saveexec_b64 s[26:27], s[26:27]
	v_mov_b64_e32 v[118:119], s[14:15]
	s_xor_b64 exec, exec, s[26:27]
	v_lshl_add_u32 v116, v117, 8, v120
	v_mov_b64_e32 v[118:119], s[18:19]
	s_or_b64 exec, exec, s[26:27]
	v_ashrrev_i32_e32 v117, 31, v116
	v_lshlrev_b64 v[116:117], 12, v[116:117]
	v_lshl_add_u64 v[116:117], v[118:119], 0, v[116:117]
	v_lshl_add_u64 v[142:143], s[24:25], 2, v[116:117]
	v_ashrrev_i32_e32 v133, 31, v132
	v_lshl_add_u64 v[116:117], v[142:143], 0, v[0:1]
	v_mov_b32_e32 v153, v1
	v_lshlrev_b64 v[128:129], 11, v[132:133]
	v_lshl_add_u64 v[138:139], v[116:117], 0, v[152:153]
	v_lshl_add_u64 v[240:241], v[138:139], 0, v[242:243]
	global_load_dwordx4 v[188:191], v[240:241], off
	global_load_dwordx4 v[192:195], v[240:241], off offset:64
	global_load_dwordx4 v[212:215], v[240:241], off offset:512
	global_load_dwordx4 v[216:219], v[240:241], off offset:576
	v_lshl_add_u64 v[144:145], s[20:21], 0, v[128:129]
	ds_read_b128 v[134:137], v158 offset:1024
	ds_read_b128 v[128:131], v158 offset:2048
	v_mov_b32_e32 v149, v1
	s_and_b64 vcc, exec, s[8:9]
	s_waitcnt vmcnt(4) lgkmcnt(0)
	v_mov_b64_e32 v[138:139], v[172:173]
	v_mov_b64_e32 v[140:141], v[174:175]
	v_mov_b64_e32 v[124:125], v[176:177]
	v_mov_b64_e32 v[126:127], v[178:179]
	v_mov_b64_e32 v[120:121], v[180:181]
	v_mov_b64_e32 v[122:123], v[182:183]
	v_mov_b64_e32 v[116:117], v[184:185]
	v_mov_b64_e32 v[118:119], v[186:187]
	v_pk_fma_f32 v[112:113], v[112:113], v[134:135], v[138:139]
	v_pk_fma_f32 v[114:115], v[114:115], v[136:137], v[140:141]
	v_lshl_add_u64 v[134:135], v[142:143], 0, v[148:149]
	v_mov_b32_e32 v138, 0
	v_lshl_add_u64 v[136:137], v[2:3], 1, v[144:145]
	global_store_dwordx4 v[134:135], v[112:115], off
	s_cbranch_vccnz .LBB0_1676
	v_pk_mul_f32 v[138:139], v[112:113], v[112:113]
	v_pk_mul_f32 v[140:141], v[114:115], v[114:115]
	v_add_f32_e32 v138, v138, v139
	v_add_f32_e32 v138, v140, v138
	v_pk_mul_f32 v[112:113], v[128:129], v[112:113]
	v_pk_mul_f32 v[114:115], v[130:131], v[114:115]
	v_add_f32_e32 v138, v141, v138
	v_cvt_pk_bf16_f32 v112, v112, v113
	v_cvt_pk_bf16_f32 v113, v114, v115
	global_store_dwordx2 v[136:137], v[112:113], off

.LBB0_1684:
	v_add_u32_e32 v116, 32, v150
	v_mul_hi_i32 v100, v116, s61
	s_waitcnt lgkmcnt(0)
	v_lshrrev_b32_e32 v101, 31, v100
	v_ashrrev_i32_e32 v100, 11, v100
	v_add_u32_e32 v101, v100, v101
	v_mad_i32_i24 v104, v101, s48, v116
	v_cmp_lt_i32_e32 vcc, s49, v104
	s_and_saveexec_b64 s[26:27], vcc
	s_xor_b64 s[26:27], exec, s[26:27]
	v_lshlrev_b32_e32 v100, 12, v101
	s_movk_i32 s28, 0xff00
	v_add3_u32 v100, v100, v104, s28
	s_or_saveexec_b64 s[26:27], s[26:27]
	v_mov_b64_e32 v[102:103], s[14:15]
	s_xor_b64 exec, exec, s[26:27]
	v_lshl_add_u32 v100, v101, 8, v104
	v_mov_b64_e32 v[102:103], s[18:19]
	s_or_b64 exec, exec, s[26:27]
	v_ashrrev_i32_e32 v101, 31, v100
	v_lshlrev_b64 v[100:101], 12, v[100:101]
	v_lshl_add_u64 v[100:101], v[102:103], 0, v[100:101]
	v_lshl_add_u64 v[126:127], s[24:25], 2, v[100:101]
	v_ashrrev_i32_e32 v117, 31, v116
	v_lshl_add_u64 v[100:101], v[126:127], 0, v[0:1]
	v_mov_b32_e32 v153, v1
	v_lshlrev_b64 v[112:113], 11, v[116:117]
	v_lshl_add_u64 v[122:123], v[100:101], 0, v[152:153]
	v_lshl_add_u64 v[240:241], v[122:123], 0, v[242:243]
	global_load_dwordx4 v[172:175], v[240:241], off
	global_load_dwordx4 v[176:179], v[240:241], off offset:64
	global_load_dwordx4 v[180:183], v[240:241], off offset:512
	global_load_dwordx4 v[184:187], v[240:241], off offset:576
	v_lshl_add_u64 v[128:129], s[20:21], 0, v[112:113]
	ds_read_b128 v[118:121], v158 offset:1024
	ds_read_b128 v[112:115], v158 offset:2048
	v_mov_b32_e32 v149, v1
	s_and_b64 vcc, exec, s[8:9]
	s_waitcnt vmcnt(4) lgkmcnt(0)
	v_mov_b64_e32 v[122:123], v[188:189]
	v_mov_b64_e32 v[124:125], v[190:191]
	v_mov_b64_e32 v[108:109], v[192:193]
	v_mov_b64_e32 v[110:111], v[194:195]
	v_mov_b64_e32 v[104:105], v[212:213]
	v_mov_b64_e32 v[106:107], v[214:215]
	v_mov_b64_e32 v[100:101], v[216:217]
	v_mov_b64_e32 v[102:103], v[218:219]
	v_pk_fma_f32 v[96:97], v[96:97], v[118:119], v[122:123]
	v_pk_fma_f32 v[98:99], v[98:99], v[120:121], v[124:125]
	v_lshl_add_u64 v[118:119], v[126:127], 0, v[148:149]
	v_mov_b32_e32 v122, 0
	v_lshl_add_u64 v[120:121], v[2:3], 1, v[128:129]
	global_store_dwordx4 v[118:119], v[96:99], off
	s_cbranch_vccnz .LBB0_1690
	v_pk_mul_f32 v[122:123], v[96:97], v[96:97]
	v_pk_mul_f32 v[124:125], v[98:99], v[98:99]
	v_add_f32_e32 v122, v122, v123
	v_add_f32_e32 v122, v124, v122
	v_pk_mul_f32 v[96:97], v[112:113], v[96:97]
	v_pk_mul_f32 v[98:99], v[114:115], v[98:99]
	v_add_f32_e32 v122, v125, v122
	v_cvt_pk_bf16_f32 v96, v96, v97
	v_cvt_pk_bf16_f32 v97, v98, v99
	global_store_dwordx2 v[120:121], v[96:97], off

.LBB0_1698:
	v_add_u32_e32 v100, 48, v150
	v_mul_hi_i32 v84, v100, s61
	s_waitcnt lgkmcnt(0)
	v_lshrrev_b32_e32 v85, 31, v84
	v_ashrrev_i32_e32 v84, 11, v84
	v_add_u32_e32 v85, v84, v85
	v_mad_i32_i24 v88, v85, s48, v100
	v_cmp_lt_i32_e32 vcc, s49, v88
	s_and_saveexec_b64 s[26:27], vcc
	s_xor_b64 s[26:27], exec, s[26:27]
	v_lshlrev_b32_e32 v84, 12, v85
	s_movk_i32 s28, 0xff00
	v_add3_u32 v84, v84, v88, s28
	s_or_saveexec_b64 s[26:27], s[26:27]
	v_mov_b64_e32 v[86:87], s[14:15]
	s_xor_b64 exec, exec, s[26:27]
	v_lshl_add_u32 v84, v85, 8, v88
	v_mov_b64_e32 v[86:87], s[18:19]
	s_or_b64 exec, exec, s[26:27]
	v_ashrrev_i32_e32 v85, 31, v84
	v_lshlrev_b64 v[84:85], 12, v[84:85]
	v_lshl_add_u64 v[84:85], v[86:87], 0, v[84:85]
	v_lshl_add_u64 v[110:111], s[24:25], 2, v[84:85]
	v_ashrrev_i32_e32 v101, 31, v100
	v_lshl_add_u64 v[84:85], v[110:111], 0, v[0:1]
	v_mov_b32_e32 v153, v1
	v_lshlrev_b64 v[96:97], 11, v[100:101]
	v_lshl_add_u64 v[106:107], v[84:85], 0, v[152:153]
	v_lshl_add_u64 v[240:241], v[106:107], 0, v[244:245]
	global_load_dwordx4 v[188:191], v[240:241], off
	global_load_dwordx4 v[192:195], v[240:241], off offset:64
	global_load_dwordx4 v[212:215], v[240:241], off offset:512
	global_load_dwordx4 v[216:219], v[240:241], off offset:576
	v_lshl_add_u64 v[112:113], s[20:21], 0, v[96:97]
	ds_read_b128 v[102:105], v158 offset:1024
	ds_read_b128 v[96:99], v158 offset:2048
	v_mov_b32_e32 v149, v1
	s_and_b64 vcc, exec, s[8:9]
	s_waitcnt vmcnt(4) lgkmcnt(0)
	v_mov_b64_e32 v[106:107], v[172:173]
	v_mov_b64_e32 v[108:109], v[174:175]
	v_mov_b64_e32 v[92:93], v[176:177]
	v_mov_b64_e32 v[94:95], v[178:179]
	v_mov_b64_e32 v[88:89], v[180:181]
	v_mov_b64_e32 v[90:91], v[182:183]
	v_mov_b64_e32 v[84:85], v[184:185]
	v_mov_b64_e32 v[86:87], v[186:187]
	v_pk_fma_f32 v[80:81], v[80:81], v[102:103], v[106:107]
	v_pk_fma_f32 v[82:83], v[82:83], v[104:105], v[108:109]
	v_lshl_add_u64 v[102:103], v[110:111], 0, v[148:149]
	v_mov_b32_e32 v106, 0
	v_lshl_add_u64 v[104:105], v[2:3], 1, v[112:113]
	global_store_dwordx4 v[102:103], v[80:83], off
	s_cbranch_vccnz .LBB0_1704
	v_pk_mul_f32 v[106:107], v[80:81], v[80:81]
	v_pk_mul_f32 v[108:109], v[82:83], v[82:83]
	v_add_f32_e32 v106, v106, v107
	v_add_f32_e32 v106, v108, v106
	v_pk_mul_f32 v[80:81], v[96:97], v[80:81]
	v_pk_mul_f32 v[82:83], v[98:99], v[82:83]
	v_add_f32_e32 v106, v109, v106
	v_cvt_pk_bf16_f32 v80, v80, v81
	v_cvt_pk_bf16_f32 v81, v82, v83
	global_store_dwordx2 v[104:105], v[80:81], off

.LBB0_1712:
	s_and_b64 vcc, exec, s[10:11]
	s_cbranch_vccnz .LBB0_1611
	v_add_u32_e32 v84, 0x80, v150
	v_mul_hi_i32 v68, v84, s61
	s_waitcnt lgkmcnt(0)
	v_lshrrev_b32_e32 v69, 31, v68
	v_ashrrev_i32_e32 v68, 11, v68
	v_add_u32_e32 v69, v68, v69
	v_mad_i32_i24 v72, v69, s48, v84
	v_cmp_lt_i32_e32 vcc, s49, v72
	s_and_saveexec_b64 s[10:11], vcc
	s_xor_b64 s[10:11], exec, s[10:11]
	v_lshlrev_b32_e32 v68, 12, v69
	s_movk_i32 s26, 0xff00
	v_add3_u32 v68, v68, v72, s26
	s_or_saveexec_b64 s[10:11], s[10:11]
	v_mov_b64_e32 v[70:71], s[14:15]
	s_xor_b64 exec, exec, s[10:11]
	v_lshl_add_u32 v68, v69, 8, v72
	v_mov_b64_e32 v[70:71], s[18:19]
	s_or_b64 exec, exec, s[10:11]
	v_ashrrev_i32_e32 v69, 31, v68
	v_lshlrev_b64 v[68:69], 12, v[68:69]
	v_lshl_add_u64 v[68:69], v[70:71], 0, v[68:69]
	v_lshl_add_u64 v[94:95], s[24:25], 2, v[68:69]
	v_ashrrev_i32_e32 v85, 31, v84
	v_lshl_add_u64 v[68:69], v[94:95], 0, v[0:1]
	v_mov_b32_e32 v153, v1
	v_lshlrev_b64 v[80:81], 11, v[84:85]
	v_lshl_add_u64 v[90:91], v[68:69], 0, v[152:153]
	v_lshl_add_u64 v[240:241], v[90:91], 0, v[242:243]
	global_load_dwordx4 v[172:175], v[240:241], off
	global_load_dwordx4 v[176:179], v[240:241], off offset:64
	global_load_dwordx4 v[180:183], v[240:241], off offset:512
	global_load_dwordx4 v[184:187], v[240:241], off offset:576
	v_lshl_add_u64 v[96:97], s[20:21], 0, v[80:81]
	ds_read_b128 v[86:89], v158 offset:1024
	ds_read_b128 v[80:83], v158 offset:2048
	v_mov_b32_e32 v149, v1
	s_and_b64 vcc, exec, s[8:9]
	s_waitcnt vmcnt(4) lgkmcnt(0)
	v_mov_b64_e32 v[90:91], v[188:189]
	v_mov_b64_e32 v[92:93], v[190:191]
	v_mov_b64_e32 v[76:77], v[192:193]
	v_mov_b64_e32 v[78:79], v[194:195]
	v_mov_b64_e32 v[72:73], v[212:213]
	v_mov_b64_e32 v[74:75], v[214:215]
	v_mov_b64_e32 v[68:69], v[216:217]
	v_mov_b64_e32 v[70:71], v[218:219]
	v_pk_fma_f32 v[64:65], v[64:65], v[86:87], v[90:91]
	v_pk_fma_f32 v[66:67], v[66:67], v[88:89], v[92:93]
	v_lshl_add_u64 v[86:87], v[94:95], 0, v[148:149]
	v_mov_b32_e32 v90, 0
	v_lshl_add_u64 v[88:89], v[2:3], 1, v[96:97]
	global_store_dwordx4 v[86:87], v[64:67], off
	s_cbranch_vccnz .LBB0_1719
	v_pk_mul_f32 v[90:91], v[64:65], v[64:65]
	v_pk_mul_f32 v[92:93], v[66:67], v[66:67]
	v_add_f32_e32 v90, v90, v91
	v_add_f32_e32 v90, v92, v90
	v_pk_mul_f32 v[64:65], v[80:81], v[64:65]
	v_pk_mul_f32 v[66:67], v[82:83], v[66:67]
	v_add_f32_e32 v90, v93, v90
	v_cvt_pk_bf16_f32 v64, v64, v65
	v_cvt_pk_bf16_f32 v65, v66, v67
	global_store_dwordx2 v[88:89], v[64:65], off

.LBB0_1727:
	v_add_u32_e32 v68, 0x90, v150
	v_mul_hi_i32 v52, v68, s61
	s_waitcnt lgkmcnt(0)
	v_lshrrev_b32_e32 v53, 31, v52
	v_ashrrev_i32_e32 v52, 11, v52
	v_add_u32_e32 v53, v52, v53
	v_mad_i32_i24 v56, v53, s48, v68
	v_cmp_lt_i32_e32 vcc, s49, v56
	s_and_saveexec_b64 s[10:11], vcc
	s_xor_b64 s[10:11], exec, s[10:11]
	v_lshlrev_b32_e32 v52, 12, v53
	s_movk_i32 s26, 0xff00
	v_add3_u32 v52, v52, v56, s26
	s_or_saveexec_b64 s[10:11], s[10:11]
	v_mov_b64_e32 v[54:55], s[14:15]
	s_xor_b64 exec, exec, s[10:11]
	v_lshl_add_u32 v52, v53, 8, v56
	v_mov_b64_e32 v[54:55], s[18:19]
	s_or_b64 exec, exec, s[10:11]
	v_ashrrev_i32_e32 v53, 31, v52
	v_lshlrev_b64 v[52:53], 12, v[52:53]
	v_lshl_add_u64 v[52:53], v[54:55], 0, v[52:53]
	v_lshl_add_u64 v[78:79], s[24:25], 2, v[52:53]
	v_ashrrev_i32_e32 v69, 31, v68
	v_lshl_add_u64 v[52:53], v[78:79], 0, v[0:1]
	v_mov_b32_e32 v153, v1
	v_lshlrev_b64 v[64:65], 11, v[68:69]
	v_lshl_add_u64 v[74:75], v[52:53], 0, v[152:153]
	v_lshl_add_u64 v[240:241], v[74:75], 0, v[242:243]
	global_load_dwordx4 v[188:191], v[240:241], off
	global_load_dwordx4 v[192:195], v[240:241], off offset:64
	global_load_dwordx4 v[212:215], v[240:241], off offset:512
	global_load_dwordx4 v[216:219], v[240:241], off offset:576
	v_lshl_add_u64 v[80:81], s[20:21], 0, v[64:65]
	ds_read_b128 v[70:73], v158 offset:1024
	ds_read_b128 v[64:67], v158 offset:2048
	v_mov_b32_e32 v149, v1
	s_and_b64 vcc, exec, s[8:9]
	s_waitcnt vmcnt(4) lgkmcnt(0)
	v_mov_b64_e32 v[74:75], v[172:173]
	v_mov_b64_e32 v[76:77], v[174:175]
	v_mov_b64_e32 v[60:61], v[176:177]
	v_mov_b64_e32 v[62:63], v[178:179]
	v_mov_b64_e32 v[56:57], v[180:181]
	v_mov_b64_e32 v[58:59], v[182:183]
	v_mov_b64_e32 v[52:53], v[184:185]
	v_mov_b64_e32 v[54:55], v[186:187]
	v_pk_fma_f32 v[48:49], v[48:49], v[70:71], v[74:75]
	v_pk_fma_f32 v[50:51], v[50:51], v[72:73], v[76:77]
	v_lshl_add_u64 v[70:71], v[78:79], 0, v[148:149]
	v_mov_b32_e32 v74, 0
	v_lshl_add_u64 v[72:73], v[2:3], 1, v[80:81]
	global_store_dwordx4 v[70:71], v[48:51], off
	s_cbranch_vccnz .LBB0_1733
	v_pk_mul_f32 v[74:75], v[48:49], v[48:49]
	v_pk_mul_f32 v[76:77], v[50:51], v[50:51]
	v_add_f32_e32 v74, v74, v75
	v_add_f32_e32 v74, v76, v74
	v_pk_mul_f32 v[48:49], v[64:65], v[48:49]
	v_pk_mul_f32 v[50:51], v[66:67], v[50:51]
	v_add_f32_e32 v74, v77, v74
	v_cvt_pk_bf16_f32 v48, v48, v49
	v_cvt_pk_bf16_f32 v49, v50, v51
	global_store_dwordx2 v[72:73], v[48:49], off

.LBB0_1741:
	v_add_u32_e32 v52, 0xa0, v150
	v_mul_hi_i32 v36, v52, s61
	s_waitcnt lgkmcnt(0)
	v_lshrrev_b32_e32 v37, 31, v36
	v_ashrrev_i32_e32 v36, 11, v36
	v_add_u32_e32 v37, v36, v37
	v_mad_i32_i24 v40, v37, s48, v52
	v_cmp_lt_i32_e32 vcc, s49, v40
	s_and_saveexec_b64 s[10:11], vcc
	s_xor_b64 s[10:11], exec, s[10:11]
	v_lshlrev_b32_e32 v36, 12, v37
	s_movk_i32 s26, 0xff00
	v_add3_u32 v36, v36, v40, s26
	s_or_saveexec_b64 s[10:11], s[10:11]
	v_mov_b64_e32 v[38:39], s[14:15]
	s_xor_b64 exec, exec, s[10:11]
	v_lshl_add_u32 v36, v37, 8, v40
	v_mov_b64_e32 v[38:39], s[18:19]
	s_or_b64 exec, exec, s[10:11]
	v_ashrrev_i32_e32 v37, 31, v36
	v_lshlrev_b64 v[36:37], 12, v[36:37]
	v_lshl_add_u64 v[36:37], v[38:39], 0, v[36:37]
	v_lshl_add_u64 v[62:63], s[24:25], 2, v[36:37]
	v_ashrrev_i32_e32 v53, 31, v52
	v_lshl_add_u64 v[36:37], v[62:63], 0, v[0:1]
	v_mov_b32_e32 v153, v1
	v_lshlrev_b64 v[48:49], 11, v[52:53]
	v_lshl_add_u64 v[58:59], v[36:37], 0, v[152:153]
	v_lshl_add_u64 v[240:241], v[58:59], 0, v[242:243]
	global_load_dwordx4 v[172:175], v[240:241], off
	global_load_dwordx4 v[176:179], v[240:241], off offset:64
	global_load_dwordx4 v[180:183], v[240:241], off offset:512
	global_load_dwordx4 v[184:187], v[240:241], off offset:576
	v_lshl_add_u64 v[64:65], s[20:21], 0, v[48:49]
	ds_read_b128 v[54:57], v158 offset:1024
	ds_read_b128 v[48:51], v158 offset:2048
	v_mov_b32_e32 v149, v1
	s_and_b64 vcc, exec, s[8:9]
	s_waitcnt vmcnt(4) lgkmcnt(0)
	v_mov_b64_e32 v[58:59], v[188:189]
	v_mov_b64_e32 v[60:61], v[190:191]
	v_mov_b64_e32 v[44:45], v[192:193]
	v_mov_b64_e32 v[46:47], v[194:195]
	v_mov_b64_e32 v[40:41], v[212:213]
	v_mov_b64_e32 v[42:43], v[214:215]
	v_mov_b64_e32 v[36:37], v[216:217]
	v_mov_b64_e32 v[38:39], v[218:219]
	v_pk_fma_f32 v[32:33], v[32:33], v[54:55], v[58:59]
	v_pk_fma_f32 v[34:35], v[34:35], v[56:57], v[60:61]
	v_lshl_add_u64 v[54:55], v[62:63], 0, v[148:149]
	v_mov_b32_e32 v58, 0
	v_lshl_add_u64 v[56:57], v[2:3], 1, v[64:65]
	global_store_dwordx4 v[54:55], v[32:35], off
	s_cbranch_vccnz .LBB0_1747
	v_pk_mul_f32 v[58:59], v[32:33], v[32:33]
	v_pk_mul_f32 v[60:61], v[34:35], v[34:35]
	v_add_f32_e32 v58, v58, v59
	v_add_f32_e32 v58, v60, v58
	v_pk_mul_f32 v[32:33], v[48:49], v[32:33]
	v_pk_mul_f32 v[34:35], v[50:51], v[34:35]
	v_add_f32_e32 v58, v61, v58
	v_cvt_pk_bf16_f32 v32, v32, v33
	v_cvt_pk_bf16_f32 v33, v34, v35
	global_store_dwordx2 v[56:57], v[32:33], off

.LBB0_1755:
	v_add_u32_e32 v36, 0xb0, v150
	v_mul_hi_i32 v20, v36, s61
	s_waitcnt lgkmcnt(0)
	v_lshrrev_b32_e32 v21, 31, v20
	v_ashrrev_i32_e32 v20, 11, v20
	v_add_u32_e32 v21, v20, v21
	v_mad_i32_i24 v24, v21, s48, v36
	v_cmp_lt_i32_e32 vcc, s49, v24
	s_and_saveexec_b64 s[10:11], vcc
	s_xor_b64 s[10:11], exec, s[10:11]
	v_lshlrev_b32_e32 v20, 12, v21
	s_movk_i32 s26, 0xff00
	v_add3_u32 v20, v20, v24, s26
	s_or_saveexec_b64 s[10:11], s[10:11]
	v_mov_b64_e32 v[22:23], s[14:15]
	s_xor_b64 exec, exec, s[10:11]
	v_lshl_add_u32 v20, v21, 8, v24
	v_mov_b64_e32 v[22:23], s[18:19]
	s_or_b64 exec, exec, s[10:11]
	v_ashrrev_i32_e32 v21, 31, v20
	v_lshlrev_b64 v[20:21], 12, v[20:21]
	v_lshl_add_u64 v[20:21], v[22:23], 0, v[20:21]
	v_lshl_add_u64 v[38:39], s[24:25], 2, v[20:21]
	v_lshl_add_u64 v[20:21], v[38:39], 0, v[0:1]
	v_mov_b32_e32 v153, v1
	v_lshl_add_u64 v[20:21], v[20:21], 0, v[152:153]
	s_nop 0
	ds_read_b128 v[46:49], v158 offset:1024
	ds_read_b128 v[32:35], v158 offset:2048
	v_ashrrev_i32_e32 v37, 31, v36
	v_lshlrev_b64 v[40:41], 11, v[36:37]
	v_mov_b32_e32 v149, v1
	v_lshl_add_u64 v[50:51], s[20:21], 0, v[40:41]
	v_mov_b32_e32 v0, 0
	s_and_b64 vcc, exec, s[8:9]
	v_lshl_add_u64 v[40:41], v[38:39], 0, v[148:149]
	v_lshl_add_u64 v[38:39], v[2:3], 1, v[50:51]
	s_waitcnt vmcnt(0) lgkmcnt(0)
	v_mov_b64_e32 v[42:43], v[172:173]
	v_mov_b64_e32 v[44:45], v[174:175]
	v_mov_b64_e32 v[28:29], v[176:177]
	v_mov_b64_e32 v[30:31], v[178:179]
	v_mov_b64_e32 v[24:25], v[180:181]
	v_mov_b64_e32 v[26:27], v[182:183]
	v_mov_b64_e32 v[20:21], v[184:185]
	v_mov_b64_e32 v[22:23], v[186:187]
	v_pk_fma_f32 v[16:17], v[16:17], v[46:47], v[42:43]
	v_pk_fma_f32 v[18:19], v[18:19], v[48:49], v[44:45]
	global_store_dwordx4 v[40:41], v[16:19], off
	s_cbranch_vccnz .LBB0_1761
	v_pk_mul_f32 v[2:3], v[16:17], v[16:17]
	v_pk_mul_f32 v[42:43], v[18:19], v[18:19]
	v_add_f32_e32 v0, v2, v3
	v_add_f32_e32 v0, v42, v0
	v_pk_mul_f32 v[2:3], v[32:33], v[16:17]
	v_pk_mul_f32 v[16:17], v[34:35], v[18:19]
	v_add_f32_e32 v0, v43, v0
	v_cvt_pk_bf16_f32 v2, v2, v3
	v_cvt_pk_bf16_f32 v3, v16, v17
	global_store_dwordx2 v[38:39], v[2:3], off
